# branch-merge GEMM epilogue: drop 240 redundant canonicalizing v_max x,x feeding the 1e-18 clamp (same value for all non-signalling inputs)
# baseline (speedup 1.0000x reference)
; __device__ __forceinline__ float bflo(unsigned w) { return __uint_as_float(w << 16); }
; __device__ __forceinline__ float bfhi(unsigned w) { return __uint_as_float(w & 0xffff0000u); }
;     __device__ __forceinline__ bool fused(f32x4 (&acc)[2][2][4][2], const Unit& u, int wr, int wc, int fr, int fq) const {
;     ...
;                     const u32x4 ga = gav[m][bj]; float s[8];
;                     s[0] = bflo(ga.x); s[1] = bfhi(ga.x); s[2] = bflo(ga.y); s[3] = bfhi(ga.y); s[4] = bflo(ga.z); s[5] = bfhi(ga.z); s[6] = bflo(ga.w); s[7] = bfhi(ga.w);
; #pragma unroll
;                     for (int j = 0; j < 8; ++j) s[j] = fmaxf(s[j], 1e-18f);
;                     if (br < 2) { const u32x4 gb = gbv[m][bj]; float d[8];
;                         d[0] = bflo(gb.x); d[1] = bfhi(gb.x); d[2] = bflo(gb.y); d[3] = bfhi(gb.y); d[4] = bflo(gb.z); d[5] = bfhi(gb.z); d[6] = bflo(gb.w); d[7] = bfhi(gb.w);
; #pragma unroll
;                         for (int j = 0; j < 8; ++j) s[j] *= __builtin_amdgcn_rcpf(fmaxf(d[j], 1e-18f)); }
;                     f32x4 v0 = acc[ai][bj][m][0], v1 = acc[ai][bj][m][1];
;                     v0[0] *= s[0]; v0[1] *= s[1]; v0[2] *= s[2]; v0[3] *= s[3]; v1[0] *= s[4]; v1[1] *= s[5]; v1[2] *= s[6]; v1[3] *= s[7];
;                     if (br < 2) { acc[ai][bj][m][0] = v0; acc[ai][bj][m][1] = v1; }
.LBB0_189:
	s_waitcnt vmcnt(0)
	v_lshlrev_b32_e32 v3, 16, v194
	v_and_b32_e32 v5, 0xffff0000, v194
	v_lshlrev_b32_e32 v198, 16, v195
	v_max_f32_e32 v194, 0x219392ef, v3
	v_and_b32_e32 v199, 0xffff0000, v195
	v_max_f32_e32 v195, 0x219392ef, v5
	v_lshlrev_b32_e32 v200, 16, v196
	v_and_b32_e32 v201, 0xffff0000, v196
	v_max_f32_e32 v196, 0x219392ef, v198
	v_lshlrev_b32_e32 v208, 16, v197
	v_and_b32_e32 v209, 0xffff0000, v197
	v_max_f32_e32 v197, 0x219392ef, v199
	v_max_f32_e32 v198, 0x219392ef, v200
	v_max_f32_e32 v199, 0x219392ef, v201
	v_max_f32_e32 v200, 0x219392ef, v208
	v_max_f32_e32 v3, v209, v209
	s_and_b64 vcc, exec, s[42:43]
	v_max_f32_e32 v201, 0x219392ef, v3
	s_cbranch_vccnz .LBB0_191
	v_lshlrev_b32_e32 v3, 16, v162
	v_and_b32_e32 v5, 0xffff0000, v162
	v_max_f32_e32 v3, 0x219392ef, v3
	v_rcp_f32_e32 v208, v3
	v_lshlrev_b32_e32 v210, 16, v163
	v_max_f32_e32 v3, 0x219392ef, v5
	v_rcp_f32_e32 v209, v3
	v_and_b32_e32 v211, 0xffff0000, v163
	v_max_f32_e32 v3, 0x219392ef, v210
	v_rcp_f32_e32 v210, v3
	v_lshlrev_b32_e32 v212, 16, v164
	v_max_f32_e32 v3, 0x219392ef, v211
	v_rcp_f32_e32 v211, v3
	v_and_b32_e32 v213, 0xffff0000, v164
	v_max_f32_e32 v3, 0x219392ef, v212
	v_rcp_f32_e32 v234, v3
	v_lshlrev_b32_e32 v229, 16, v165
	v_max_f32_e32 v3, 0x219392ef, v213
	v_rcp_f32_e32 v235, v3
	v_and_b32_e32 v231, 0xffff0000, v165
	v_max_f32_e32 v3, 0x219392ef, v229
	v_rcp_f32_e32 v212, v3
	v_max_f32_e32 v3, 0x219392ef, v231
	v_rcp_f32_e32 v213, v3
	v_pk_mul_f32 v[194:195], v[194:195], v[208:209]
	v_pk_mul_f32 v[196:197], v[196:197], v[210:211]
	v_pk_mul_f32 v[198:199], v[198:199], v[234:235]
	v_pk_mul_f32 v[200:201], v[200:201], v[212:213]

; __device__ __forceinline__ float bflo(unsigned w) { return __uint_as_float(w << 16); }
; __device__ __forceinline__ float bfhi(unsigned w) { return __uint_as_float(w & 0xffff0000u); }
;     __device__ __forceinline__ bool fused(f32x4 (&acc)[2][2][4][2], const Unit& u, int wr, int wc, int fr, int fq) const {
;     ...
;                     const u32x4 ga = gav[m][bj]; float s[8];
;                     s[0] = bflo(ga.x); s[1] = bfhi(ga.x); s[2] = bflo(ga.y); s[3] = bfhi(ga.y); s[4] = bflo(ga.z); s[5] = bfhi(ga.z); s[6] = bflo(ga.w); s[7] = bfhi(ga.w);
; #pragma unroll
;                     for (int j = 0; j < 8; ++j) s[j] = fmaxf(s[j], 1e-18f);
;                     if (br < 2) { const u32x4 gb = gbv[m][bj]; float d[8];
;                         d[0] = bflo(gb.x); d[1] = bfhi(gb.x); d[2] = bflo(gb.y); d[3] = bfhi(gb.y); d[4] = bflo(gb.z); d[5] = bfhi(gb.z); d[6] = bflo(gb.w); d[7] = bfhi(gb.w);
; #pragma unroll
;                         for (int j = 0; j < 8; ++j) s[j] *= __builtin_amdgcn_rcpf(fmaxf(d[j], 1e-18f)); }
;                     f32x4 v0 = acc[ai][bj][m][0], v1 = acc[ai][bj][m][1];
;                     v0[0] *= s[0]; v0[1] *= s[1]; v0[2] *= s[2]; v0[3] *= s[3]; v1[0] *= s[4]; v1[1] *= s[5]; v1[2] *= s[6]; v1[3] *= s[7];
;                     if (br < 2) { acc[ai][bj][m][0] = v0; acc[ai][bj][m][1] = v1; }
.LBB0_194:
	v_lshlrev_b32_e32 v3, 16, v190
	v_and_b32_e32 v5, 0xffff0000, v190
	v_lshlrev_b32_e32 v194, 16, v191
	v_max_f32_e32 v190, 0x219392ef, v3
	v_and_b32_e32 v195, 0xffff0000, v191
	v_max_f32_e32 v191, 0x219392ef, v5
	v_lshlrev_b32_e32 v196, 16, v192
	v_and_b32_e32 v197, 0xffff0000, v192
	v_max_f32_e32 v192, 0x219392ef, v194
	v_lshlrev_b32_e32 v198, 16, v193
	v_and_b32_e32 v199, 0xffff0000, v193
	v_max_f32_e32 v193, 0x219392ef, v195
	v_max_f32_e32 v194, 0x219392ef, v196
	v_max_f32_e32 v195, 0x219392ef, v197
	v_max_f32_e32 v196, 0x219392ef, v198
	v_max_f32_e32 v3, v199, v199
	v_ashrrev_i32_e32 v233, 31, v232
	v_ashrrev_i32_e32 v231, 31, v230
	v_ashrrev_i32_e32 v229, 31, v228
	s_and_b64 vcc, exec, s[42:43]
	v_max_f32_e32 v197, 0x219392ef, v3
	s_cbranch_vccnz .LBB0_196
	v_lshlrev_b32_e32 v3, 16, v158
	v_and_b32_e32 v5, 0xffff0000, v158
	v_max_f32_e32 v3, 0x219392ef, v3
	v_rcp_f32_e32 v198, v3
	v_lshlrev_b32_e32 v200, 16, v159
	v_max_f32_e32 v3, 0x219392ef, v5
	v_rcp_f32_e32 v199, v3
	v_and_b32_e32 v201, 0xffff0000, v159
	v_max_f32_e32 v3, 0x219392ef, v200
	v_rcp_f32_e32 v200, v3
	v_lshlrev_b32_e32 v208, 16, v160
	v_max_f32_e32 v3, 0x219392ef, v201
	v_rcp_f32_e32 v201, v3
	v_and_b32_e32 v209, 0xffff0000, v160
	v_max_f32_e32 v3, 0x219392ef, v208
	v_rcp_f32_e32 v208, v3
	v_lshlrev_b32_e32 v210, 16, v161
	v_max_f32_e32 v3, 0x219392ef, v209
	v_rcp_f32_e32 v209, v3
	v_and_b32_e32 v211, 0xffff0000, v161
	v_max_f32_e32 v3, 0x219392ef, v210
	v_rcp_f32_e32 v210, v3
	v_max_f32_e32 v3, 0x219392ef, v211
	v_rcp_f32_e32 v211, v3
	v_pk_mul_f32 v[190:191], v[190:191], v[198:199]
	v_pk_mul_f32 v[192:193], v[192:193], v[200:201]
	v_pk_mul_f32 v[194:195], v[194:195], v[208:209]
	v_pk_mul_f32 v[196:197], v[196:197], v[210:211]

; __device__ __forceinline__ float bflo(unsigned w) { return __uint_as_float(w << 16); }
; __device__ __forceinline__ float bfhi(unsigned w) { return __uint_as_float(w & 0xffff0000u); }
;     __device__ __forceinline__ bool fused(f32x4 (&acc)[2][2][4][2], const Unit& u, int wr, int wc, int fr, int fq) const {
;     ...
;                     const u32x4 ga = gav[m][bj]; float s[8];
;                     s[0] = bflo(ga.x); s[1] = bfhi(ga.x); s[2] = bflo(ga.y); s[3] = bfhi(ga.y); s[4] = bflo(ga.z); s[5] = bfhi(ga.z); s[6] = bflo(ga.w); s[7] = bfhi(ga.w);
; #pragma unroll
;                     for (int j = 0; j < 8; ++j) s[j] = fmaxf(s[j], 1e-18f);
;                     if (br < 2) { const u32x4 gb = gbv[m][bj]; float d[8];
;                         d[0] = bflo(gb.x); d[1] = bfhi(gb.x); d[2] = bflo(gb.y); d[3] = bfhi(gb.y); d[4] = bflo(gb.z); d[5] = bfhi(gb.z); d[6] = bflo(gb.w); d[7] = bfhi(gb.w);
; #pragma unroll
;                         for (int j = 0; j < 8; ++j) s[j] *= __builtin_amdgcn_rcpf(fmaxf(d[j], 1e-18f)); }
;                     f32x4 v0 = acc[ai][bj][m][0], v1 = acc[ai][bj][m][1];
;                     v0[0] *= s[0]; v0[1] *= s[1]; v0[2] *= s[2]; v0[3] *= s[3]; v1[0] *= s[4]; v1[1] *= s[5]; v1[2] *= s[6]; v1[3] *= s[7];
;                     if (br < 2) { acc[ai][bj][m][0] = v0; acc[ai][bj][m][1] = v1; }
.LBB0_199:
	v_lshlrev_b32_e32 v3, 16, v186
	v_and_b32_e32 v5, 0xffff0000, v186
	v_lshlrev_b32_e32 v190, 16, v187
	v_max_f32_e32 v186, 0x219392ef, v3
	v_and_b32_e32 v191, 0xffff0000, v187
	v_max_f32_e32 v187, 0x219392ef, v5
	v_lshlrev_b32_e32 v192, 16, v188
	v_and_b32_e32 v193, 0xffff0000, v188
	v_max_f32_e32 v188, 0x219392ef, v190
	v_lshlrev_b32_e32 v194, 16, v189
	v_and_b32_e32 v195, 0xffff0000, v189
	v_max_f32_e32 v189, 0x219392ef, v191
	v_max_f32_e32 v190, 0x219392ef, v192
	v_max_f32_e32 v191, 0x219392ef, v193
	s_andn2_b64 vcc, exec, s[4:5]
	v_max_f32_e32 v192, 0x219392ef, v194
	v_max_f32_e32 v3, v195, v195
	s_and_b64 vcc, exec, s[42:43]
	v_max_f32_e32 v193, 0x219392ef, v3
	s_cbranch_vccnz .LBB0_201
	v_lshlrev_b32_e32 v3, 16, v154
	v_and_b32_e32 v5, 0xffff0000, v154
	v_max_f32_e32 v3, 0x219392ef, v3
	v_rcp_f32_e32 v194, v3
	v_lshlrev_b32_e32 v196, 16, v155
	v_max_f32_e32 v3, 0x219392ef, v5
	v_rcp_f32_e32 v195, v3
	v_and_b32_e32 v197, 0xffff0000, v155
	v_max_f32_e32 v3, 0x219392ef, v196
	v_rcp_f32_e32 v196, v3
	v_lshlrev_b32_e32 v198, 16, v156
	v_max_f32_e32 v3, 0x219392ef, v197
	v_rcp_f32_e32 v197, v3
	v_and_b32_e32 v199, 0xffff0000, v156
	v_max_f32_e32 v3, 0x219392ef, v198
	v_rcp_f32_e32 v198, v3
	v_lshlrev_b32_e32 v200, 16, v157
	v_max_f32_e32 v3, 0x219392ef, v199
	v_rcp_f32_e32 v199, v3
	v_and_b32_e32 v201, 0xffff0000, v157
	v_max_f32_e32 v3, 0x219392ef, v200
	v_rcp_f32_e32 v200, v3
	v_max_f32_e32 v3, 0x219392ef, v201
	v_rcp_f32_e32 v201, v3
	v_pk_mul_f32 v[186:187], v[186:187], v[194:195]
	v_pk_mul_f32 v[188:189], v[188:189], v[196:197]
	v_pk_mul_f32 v[190:191], v[190:191], v[198:199]
	v_pk_mul_f32 v[192:193], v[192:193], v[200:201]

; __device__ __forceinline__ float bflo(unsigned w) { return __uint_as_float(w << 16); }
; __device__ __forceinline__ float bfhi(unsigned w) { return __uint_as_float(w & 0xffff0000u); }
;     __device__ __forceinline__ bool fused(f32x4 (&acc)[2][2][4][2], const Unit& u, int wr, int wc, int fr, int fq) const {
;     ...
;                     const u32x4 ga = gav[m][bj]; float s[8];
;                     s[0] = bflo(ga.x); s[1] = bfhi(ga.x); s[2] = bflo(ga.y); s[3] = bfhi(ga.y); s[4] = bflo(ga.z); s[5] = bfhi(ga.z); s[6] = bflo(ga.w); s[7] = bfhi(ga.w);
; #pragma unroll
;                     for (int j = 0; j < 8; ++j) s[j] = fmaxf(s[j], 1e-18f);
;                     if (br < 2) { const u32x4 gb = gbv[m][bj]; float d[8];
;                         d[0] = bflo(gb.x); d[1] = bfhi(gb.x); d[2] = bflo(gb.y); d[3] = bfhi(gb.y); d[4] = bflo(gb.z); d[5] = bfhi(gb.z); d[6] = bflo(gb.w); d[7] = bfhi(gb.w);
; #pragma unroll
;                         for (int j = 0; j < 8; ++j) s[j] *= __builtin_amdgcn_rcpf(fmaxf(d[j], 1e-18f)); }
;                     f32x4 v0 = acc[ai][bj][m][0], v1 = acc[ai][bj][m][1];
;                     v0[0] *= s[0]; v0[1] *= s[1]; v0[2] *= s[2]; v0[3] *= s[3]; v1[0] *= s[4]; v1[1] *= s[5]; v1[2] *= s[6]; v1[3] *= s[7];
;                     if (br < 2) { acc[ai][bj][m][0] = v0; acc[ai][bj][m][1] = v1; }
.LBB0_204:
	v_lshlrev_b32_e32 v3, 16, v182
	v_and_b32_e32 v5, 0xffff0000, v182
	v_lshlrev_b32_e32 v186, 16, v183
	v_max_f32_e32 v182, 0x219392ef, v3
	v_and_b32_e32 v187, 0xffff0000, v183
	v_max_f32_e32 v183, 0x219392ef, v5
	v_lshlrev_b32_e32 v188, 16, v184
	v_and_b32_e32 v189, 0xffff0000, v184
	v_max_f32_e32 v184, 0x219392ef, v186
	v_lshlrev_b32_e32 v190, 16, v185
	v_and_b32_e32 v191, 0xffff0000, v185
	v_max_f32_e32 v185, 0x219392ef, v187
	v_max_f32_e32 v186, 0x219392ef, v188
	v_max_f32_e32 v187, 0x219392ef, v189
	s_andn2_b64 vcc, exec, s[4:5]
	v_max_f32_e32 v188, 0x219392ef, v190
	v_max_f32_e32 v3, v191, v191
	s_and_b64 vcc, exec, s[42:43]
	v_max_f32_e32 v189, 0x219392ef, v3
	s_cbranch_vccnz .LBB0_206
	v_lshlrev_b32_e32 v3, 16, v150
	v_and_b32_e32 v5, 0xffff0000, v150
	v_max_f32_e32 v3, 0x219392ef, v3
	v_rcp_f32_e32 v190, v3
	v_lshlrev_b32_e32 v192, 16, v151
	v_max_f32_e32 v3, 0x219392ef, v5
	v_rcp_f32_e32 v191, v3
	v_and_b32_e32 v193, 0xffff0000, v151
	v_max_f32_e32 v3, 0x219392ef, v192
	v_rcp_f32_e32 v192, v3
	v_lshlrev_b32_e32 v196, 16, v152
	v_max_f32_e32 v3, 0x219392ef, v193
	v_rcp_f32_e32 v193, v3
	v_and_b32_e32 v197, 0xffff0000, v152
	v_max_f32_e32 v3, 0x219392ef, v196
	v_rcp_f32_e32 v196, v3
	v_lshlrev_b32_e32 v198, 16, v153
	v_max_f32_e32 v3, 0x219392ef, v197
	v_rcp_f32_e32 v197, v3
	v_and_b32_e32 v199, 0xffff0000, v153
	v_max_f32_e32 v3, 0x219392ef, v198
	v_rcp_f32_e32 v198, v3
	v_max_f32_e32 v3, 0x219392ef, v199
	v_rcp_f32_e32 v199, v3
	v_pk_mul_f32 v[182:183], v[182:183], v[190:191]
	v_pk_mul_f32 v[184:185], v[184:185], v[192:193]
	v_pk_mul_f32 v[186:187], v[186:187], v[196:197]
	v_pk_mul_f32 v[188:189], v[188:189], v[198:199]

; __device__ __forceinline__ float bflo(unsigned w) { return __uint_as_float(w << 16); }
; __device__ __forceinline__ float bfhi(unsigned w) { return __uint_as_float(w & 0xffff0000u); }
;     __device__ __forceinline__ bool fused(f32x4 (&acc)[2][2][4][2], const Unit& u, int wr, int wc, int fr, int fq) const {
;     ...
;                     const u32x4 ga = gav[m][bj]; float s[8];
;                     s[0] = bflo(ga.x); s[1] = bfhi(ga.x); s[2] = bflo(ga.y); s[3] = bfhi(ga.y); s[4] = bflo(ga.z); s[5] = bfhi(ga.z); s[6] = bflo(ga.w); s[7] = bfhi(ga.w);
; #pragma unroll
;                     for (int j = 0; j < 8; ++j) s[j] = fmaxf(s[j], 1e-18f);
;                     if (br < 2) { const u32x4 gb = gbv[m][bj]; float d[8];
;                         d[0] = bflo(gb.x); d[1] = bfhi(gb.x); d[2] = bflo(gb.y); d[3] = bfhi(gb.y); d[4] = bflo(gb.z); d[5] = bfhi(gb.z); d[6] = bflo(gb.w); d[7] = bfhi(gb.w);
; #pragma unroll
;                         for (int j = 0; j < 8; ++j) s[j] *= __builtin_amdgcn_rcpf(fmaxf(d[j], 1e-18f)); }
;                     f32x4 v0 = acc[ai][bj][m][0], v1 = acc[ai][bj][m][1];
;                     v0[0] *= s[0]; v0[1] *= s[1]; v0[2] *= s[2]; v0[3] *= s[3]; v1[0] *= s[4]; v1[1] *= s[5]; v1[2] *= s[6]; v1[3] *= s[7];
;                     if (br < 2) { acc[ai][bj][m][0] = v0; acc[ai][bj][m][1] = v1; }
.LBB0_209:
	v_lshlrev_b32_e32 v3, 16, v178
	v_and_b32_e32 v5, 0xffff0000, v178
	v_lshlrev_b32_e32 v182, 16, v179
	v_max_f32_e32 v178, 0x219392ef, v3
	v_and_b32_e32 v183, 0xffff0000, v179
	v_max_f32_e32 v179, 0x219392ef, v5
	v_lshlrev_b32_e32 v184, 16, v180
	v_and_b32_e32 v185, 0xffff0000, v180
	v_max_f32_e32 v180, 0x219392ef, v182
	v_lshlrev_b32_e32 v186, 16, v181
	v_and_b32_e32 v187, 0xffff0000, v181
	v_max_f32_e32 v181, 0x219392ef, v183
	v_max_f32_e32 v182, 0x219392ef, v184
	v_max_f32_e32 v183, 0x219392ef, v185
	s_andn2_b64 vcc, exec, s[4:5]
	v_max_f32_e32 v184, 0x219392ef, v186
	v_max_f32_e32 v3, v187, v187
	s_and_b64 vcc, exec, s[42:43]
	v_max_f32_e32 v185, 0x219392ef, v3
	s_cbranch_vccnz .LBB0_211
	v_lshlrev_b32_e32 v3, 16, v146
	v_and_b32_e32 v5, 0xffff0000, v146
	v_max_f32_e32 v3, 0x219392ef, v3
	v_rcp_f32_e32 v186, v3
	v_lshlrev_b32_e32 v188, 16, v147
	v_max_f32_e32 v3, 0x219392ef, v5
	v_rcp_f32_e32 v187, v3
	v_and_b32_e32 v189, 0xffff0000, v147
	v_max_f32_e32 v3, 0x219392ef, v188
	v_rcp_f32_e32 v188, v3
	v_lshlrev_b32_e32 v190, 16, v148
	v_max_f32_e32 v3, 0x219392ef, v189
	v_rcp_f32_e32 v189, v3
	v_and_b32_e32 v191, 0xffff0000, v148
	v_max_f32_e32 v3, 0x219392ef, v190
	v_rcp_f32_e32 v190, v3
	v_lshlrev_b32_e32 v192, 16, v149
	v_max_f32_e32 v3, 0x219392ef, v191
	v_rcp_f32_e32 v191, v3
	v_and_b32_e32 v193, 0xffff0000, v149
	v_max_f32_e32 v3, 0x219392ef, v192
	v_rcp_f32_e32 v192, v3
	v_max_f32_e32 v3, 0x219392ef, v193
	v_rcp_f32_e32 v193, v3
	v_pk_mul_f32 v[178:179], v[178:179], v[186:187]
	v_pk_mul_f32 v[180:181], v[180:181], v[188:189]
	v_pk_mul_f32 v[182:183], v[182:183], v[190:191]
	v_pk_mul_f32 v[184:185], v[184:185], v[192:193]

; __device__ __forceinline__ float bflo(unsigned w) { return __uint_as_float(w << 16); }
; __device__ __forceinline__ float bfhi(unsigned w) { return __uint_as_float(w & 0xffff0000u); }
;     __device__ __forceinline__ bool fused(f32x4 (&acc)[2][2][4][2], const Unit& u, int wr, int wc, int fr, int fq) const {
;     ...
;                     const u32x4 ga = gav[m][bj]; float s[8];
;                     s[0] = bflo(ga.x); s[1] = bfhi(ga.x); s[2] = bflo(ga.y); s[3] = bfhi(ga.y); s[4] = bflo(ga.z); s[5] = bfhi(ga.z); s[6] = bflo(ga.w); s[7] = bfhi(ga.w);
; #pragma unroll
;                     for (int j = 0; j < 8; ++j) s[j] = fmaxf(s[j], 1e-18f);
;                     if (br < 2) { const u32x4 gb = gbv[m][bj]; float d[8];
;                         d[0] = bflo(gb.x); d[1] = bfhi(gb.x); d[2] = bflo(gb.y); d[3] = bfhi(gb.y); d[4] = bflo(gb.z); d[5] = bfhi(gb.z); d[6] = bflo(gb.w); d[7] = bfhi(gb.w);
; #pragma unroll
;                         for (int j = 0; j < 8; ++j) s[j] *= __builtin_amdgcn_rcpf(fmaxf(d[j], 1e-18f)); }
;                     f32x4 v0 = acc[ai][bj][m][0], v1 = acc[ai][bj][m][1];
;                     v0[0] *= s[0]; v0[1] *= s[1]; v0[2] *= s[2]; v0[3] *= s[3]; v1[0] *= s[4]; v1[1] *= s[5]; v1[2] *= s[6]; v1[3] *= s[7];
;                     if (br < 2) { acc[ai][bj][m][0] = v0; acc[ai][bj][m][1] = v1; }
.LBB0_214:
	v_lshlrev_b32_e32 v3, 16, v174
	v_and_b32_e32 v5, 0xffff0000, v174
	v_lshlrev_b32_e32 v178, 16, v175
	v_max_f32_e32 v174, 0x219392ef, v3
	v_and_b32_e32 v179, 0xffff0000, v175
	v_max_f32_e32 v175, 0x219392ef, v5
	v_lshlrev_b32_e32 v180, 16, v176
	v_and_b32_e32 v181, 0xffff0000, v176
	v_max_f32_e32 v176, 0x219392ef, v178
	v_lshlrev_b32_e32 v182, 16, v177
	v_and_b32_e32 v183, 0xffff0000, v177
	v_max_f32_e32 v177, 0x219392ef, v179
	v_max_f32_e32 v178, 0x219392ef, v180
	v_max_f32_e32 v179, 0x219392ef, v181
	s_andn2_b64 vcc, exec, s[4:5]
	v_max_f32_e32 v180, 0x219392ef, v182
	v_max_f32_e32 v3, v183, v183
	s_and_b64 vcc, exec, s[42:43]
	v_max_f32_e32 v181, 0x219392ef, v3
	s_cbranch_vccnz .LBB0_216
	v_lshlrev_b32_e32 v3, 16, v142
	v_and_b32_e32 v5, 0xffff0000, v142
	v_max_f32_e32 v3, 0x219392ef, v3
	v_rcp_f32_e32 v182, v3
	v_lshlrev_b32_e32 v184, 16, v143
	v_max_f32_e32 v3, 0x219392ef, v5
	v_rcp_f32_e32 v183, v3
	v_and_b32_e32 v185, 0xffff0000, v143
	v_max_f32_e32 v3, 0x219392ef, v184
	v_rcp_f32_e32 v184, v3
	v_lshlrev_b32_e32 v188, 16, v144
	v_max_f32_e32 v3, 0x219392ef, v185
	v_rcp_f32_e32 v185, v3
	v_and_b32_e32 v189, 0xffff0000, v144
	v_max_f32_e32 v3, 0x219392ef, v188
	v_rcp_f32_e32 v188, v3
	v_lshlrev_b32_e32 v190, 16, v145
	v_max_f32_e32 v3, 0x219392ef, v189
	v_rcp_f32_e32 v189, v3
	v_and_b32_e32 v191, 0xffff0000, v145
	v_max_f32_e32 v3, 0x219392ef, v190
	v_rcp_f32_e32 v190, v3
	v_max_f32_e32 v3, 0x219392ef, v191
	v_rcp_f32_e32 v191, v3
	v_pk_mul_f32 v[174:175], v[174:175], v[182:183]
	v_pk_mul_f32 v[176:177], v[176:177], v[184:185]
	v_pk_mul_f32 v[178:179], v[178:179], v[188:189]
	v_pk_mul_f32 v[180:181], v[180:181], v[190:191]

; __device__ __forceinline__ float bflo(unsigned w) { return __uint_as_float(w << 16); }
; __device__ __forceinline__ float bfhi(unsigned w) { return __uint_as_float(w & 0xffff0000u); }
;     __device__ __forceinline__ bool fused(f32x4 (&acc)[2][2][4][2], const Unit& u, int wr, int wc, int fr, int fq) const {
;     ...
;                     const u32x4 ga = gav[m][bj]; float s[8];
;                     s[0] = bflo(ga.x); s[1] = bfhi(ga.x); s[2] = bflo(ga.y); s[3] = bfhi(ga.y); s[4] = bflo(ga.z); s[5] = bfhi(ga.z); s[6] = bflo(ga.w); s[7] = bfhi(ga.w);
; #pragma unroll
;                     for (int j = 0; j < 8; ++j) s[j] = fmaxf(s[j], 1e-18f);
;                     if (br < 2) { const u32x4 gb = gbv[m][bj]; float d[8];
;                         d[0] = bflo(gb.x); d[1] = bfhi(gb.x); d[2] = bflo(gb.y); d[3] = bfhi(gb.y); d[4] = bflo(gb.z); d[5] = bfhi(gb.z); d[6] = bflo(gb.w); d[7] = bfhi(gb.w);
; #pragma unroll
;                         for (int j = 0; j < 8; ++j) s[j] *= __builtin_amdgcn_rcpf(fmaxf(d[j], 1e-18f)); }
;                     f32x4 v0 = acc[ai][bj][m][0], v1 = acc[ai][bj][m][1];
;                     v0[0] *= s[0]; v0[1] *= s[1]; v0[2] *= s[2]; v0[3] *= s[3]; v1[0] *= s[4]; v1[1] *= s[5]; v1[2] *= s[6]; v1[3] *= s[7];
;                     if (br < 2) { acc[ai][bj][m][0] = v0; acc[ai][bj][m][1] = v1; }
.LBB0_219:
	v_lshlrev_b32_e32 v3, 16, v170
	v_and_b32_e32 v5, 0xffff0000, v170
	v_lshlrev_b32_e32 v174, 16, v171
	v_max_f32_e32 v170, 0x219392ef, v3
	v_and_b32_e32 v175, 0xffff0000, v171
	v_max_f32_e32 v171, 0x219392ef, v5
	v_lshlrev_b32_e32 v176, 16, v172
	v_and_b32_e32 v177, 0xffff0000, v172
	v_max_f32_e32 v172, 0x219392ef, v174
	v_lshlrev_b32_e32 v178, 16, v173
	v_and_b32_e32 v179, 0xffff0000, v173
	v_max_f32_e32 v173, 0x219392ef, v175
	v_max_f32_e32 v174, 0x219392ef, v176
	v_max_f32_e32 v175, 0x219392ef, v177
	s_andn2_b64 vcc, exec, s[4:5]
	v_max_f32_e32 v176, 0x219392ef, v178
	v_max_f32_e32 v3, v179, v179
	s_and_b64 vcc, exec, s[42:43]
	v_max_f32_e32 v177, 0x219392ef, v3
	s_cbranch_vccnz .LBB0_221
	v_lshlrev_b32_e32 v3, 16, v138
	v_and_b32_e32 v5, 0xffff0000, v138
	v_max_f32_e32 v3, 0x219392ef, v3
	v_rcp_f32_e32 v178, v3
	v_lshlrev_b32_e32 v180, 16, v139
	v_max_f32_e32 v3, 0x219392ef, v5
	v_rcp_f32_e32 v179, v3
	v_and_b32_e32 v181, 0xffff0000, v139
	v_max_f32_e32 v3, 0x219392ef, v180
	v_rcp_f32_e32 v180, v3
	v_lshlrev_b32_e32 v182, 16, v140
	v_max_f32_e32 v3, 0x219392ef, v181
	v_rcp_f32_e32 v181, v3
	v_and_b32_e32 v183, 0xffff0000, v140
	v_max_f32_e32 v3, 0x219392ef, v182
	v_rcp_f32_e32 v182, v3
	v_lshlrev_b32_e32 v184, 16, v141
	v_max_f32_e32 v3, 0x219392ef, v183
	v_rcp_f32_e32 v183, v3
	v_and_b32_e32 v185, 0xffff0000, v141
	v_max_f32_e32 v3, 0x219392ef, v184
	v_rcp_f32_e32 v184, v3
	v_max_f32_e32 v3, 0x219392ef, v185
	v_rcp_f32_e32 v185, v3
	v_pk_mul_f32 v[170:171], v[170:171], v[178:179]
	v_pk_mul_f32 v[172:173], v[172:173], v[180:181]
	v_pk_mul_f32 v[174:175], v[174:175], v[182:183]
	v_pk_mul_f32 v[176:177], v[176:177], v[184:185]

; __device__ __forceinline__ float bflo(unsigned w) { return __uint_as_float(w << 16); }
; __device__ __forceinline__ float bfhi(unsigned w) { return __uint_as_float(w & 0xffff0000u); }
;     __device__ __forceinline__ bool fused(f32x4 (&acc)[2][2][4][2], const Unit& u, int wr, int wc, int fr, int fq) const {
;     ...
;                     const u32x4 ga = gav[m][bj]; float s[8];
;                     s[0] = bflo(ga.x); s[1] = bfhi(ga.x); s[2] = bflo(ga.y); s[3] = bfhi(ga.y); s[4] = bflo(ga.z); s[5] = bfhi(ga.z); s[6] = bflo(ga.w); s[7] = bfhi(ga.w);
; #pragma unroll
;                     for (int j = 0; j < 8; ++j) s[j] = fmaxf(s[j], 1e-18f);
;                     if (br < 2) { const u32x4 gb = gbv[m][bj]; float d[8];
;                         d[0] = bflo(gb.x); d[1] = bfhi(gb.x); d[2] = bflo(gb.y); d[3] = bfhi(gb.y); d[4] = bflo(gb.z); d[5] = bfhi(gb.z); d[6] = bflo(gb.w); d[7] = bfhi(gb.w);
; #pragma unroll
;                         for (int j = 0; j < 8; ++j) s[j] *= __builtin_amdgcn_rcpf(fmaxf(d[j], 1e-18f)); }
;                     f32x4 v0 = acc[ai][bj][m][0], v1 = acc[ai][bj][m][1];
;                     v0[0] *= s[0]; v0[1] *= s[1]; v0[2] *= s[2]; v0[3] *= s[3]; v1[0] *= s[4]; v1[1] *= s[5]; v1[2] *= s[6]; v1[3] *= s[7];
;                     if (br < 2) { acc[ai][bj][m][0] = v0; acc[ai][bj][m][1] = v1; }
.LBB0_224:
	v_lshlrev_b32_e32 v3, 16, v166
	v_and_b32_e32 v5, 0xffff0000, v166
	v_lshlrev_b32_e32 v170, 16, v167
	v_max_f32_e32 v166, 0x219392ef, v3
	v_and_b32_e32 v171, 0xffff0000, v167
	v_max_f32_e32 v167, 0x219392ef, v5
	v_lshlrev_b32_e32 v172, 16, v168
	v_and_b32_e32 v173, 0xffff0000, v168
	v_max_f32_e32 v168, 0x219392ef, v170
	v_lshlrev_b32_e32 v174, 16, v169
	v_and_b32_e32 v175, 0xffff0000, v169
	v_max_f32_e32 v169, 0x219392ef, v171
	v_max_f32_e32 v170, 0x219392ef, v172
	v_max_f32_e32 v171, 0x219392ef, v173
	s_andn2_b64 vcc, exec, s[4:5]
	v_max_f32_e32 v172, 0x219392ef, v174
	v_max_f32_e32 v3, v175, v175
	s_and_b64 vcc, exec, s[42:43]
	v_max_f32_e32 v173, 0x219392ef, v3
	s_cbranch_vccnz .LBB0_226
	v_lshlrev_b32_e32 v3, 16, v134
	v_and_b32_e32 v5, 0xffff0000, v134
	v_max_f32_e32 v3, 0x219392ef, v3
	v_rcp_f32_e32 v174, v3
	v_lshlrev_b32_e32 v176, 16, v135
	v_max_f32_e32 v3, 0x219392ef, v5
	v_rcp_f32_e32 v175, v3
	v_and_b32_e32 v177, 0xffff0000, v135
	v_max_f32_e32 v3, 0x219392ef, v176
	v_rcp_f32_e32 v176, v3
	v_lshlrev_b32_e32 v180, 16, v136
	v_max_f32_e32 v3, 0x219392ef, v177
	v_rcp_f32_e32 v177, v3
	v_and_b32_e32 v181, 0xffff0000, v136
	v_max_f32_e32 v3, 0x219392ef, v180
	v_rcp_f32_e32 v180, v3
	v_lshlrev_b32_e32 v182, 16, v137
	v_max_f32_e32 v3, 0x219392ef, v181
	v_rcp_f32_e32 v181, v3
	v_and_b32_e32 v183, 0xffff0000, v137
	v_max_f32_e32 v3, 0x219392ef, v182
	v_rcp_f32_e32 v182, v3
	v_max_f32_e32 v3, 0x219392ef, v183
	v_rcp_f32_e32 v183, v3
	v_pk_mul_f32 v[166:167], v[166:167], v[174:175]
	v_pk_mul_f32 v[168:169], v[168:169], v[176:177]
	v_pk_mul_f32 v[170:171], v[170:171], v[180:181]
	v_pk_mul_f32 v[172:173], v[172:173], v[182:183]

; __device__ __forceinline__ float bflo(unsigned w) { return __uint_as_float(w << 16); }
; __device__ __forceinline__ float bfhi(unsigned w) { return __uint_as_float(w & 0xffff0000u); }
;     __device__ __forceinline__ bool fused(f32x4 (&acc)[2][2][4][2], const Unit& u, int wr, int wc, int fr, int fq) const {
;     ...
;                     const u32x4 ga = gav[m][bj]; float s[8];
;                     s[0] = bflo(ga.x); s[1] = bfhi(ga.x); s[2] = bflo(ga.y); s[3] = bfhi(ga.y); s[4] = bflo(ga.z); s[5] = bfhi(ga.z); s[6] = bflo(ga.w); s[7] = bfhi(ga.w);
; #pragma unroll
;                     for (int j = 0; j < 8; ++j) s[j] = fmaxf(s[j], 1e-18f);
;                     if (br < 2) { const u32x4 gb = gbv[m][bj]; float d[8];
;                         d[0] = bflo(gb.x); d[1] = bfhi(gb.x); d[2] = bflo(gb.y); d[3] = bfhi(gb.y); d[4] = bflo(gb.z); d[5] = bfhi(gb.z); d[6] = bflo(gb.w); d[7] = bfhi(gb.w);
; #pragma unroll
;                         for (int j = 0; j < 8; ++j) s[j] *= __builtin_amdgcn_rcpf(fmaxf(d[j], 1e-18f)); }
;                     f32x4 v0 = acc[ai][bj][m][0], v1 = acc[ai][bj][m][1];
;                     v0[0] *= s[0]; v0[1] *= s[1]; v0[2] *= s[2]; v0[3] *= s[3]; v1[0] *= s[4]; v1[1] *= s[5]; v1[2] *= s[6]; v1[3] *= s[7];
;                     if (br < 2) { acc[ai][bj][m][0] = v0; acc[ai][bj][m][1] = v1; }
.LBB0_245:
	s_waitcnt vmcnt(7)
	v_lshlrev_b32_e32 v3, 16, v194
	v_and_b32_e32 v5, 0xffff0000, v194
	v_lshlrev_b32_e32 v194, 16, v195
	v_max_f32_e32 v226, 0x219392ef, v3
	v_and_b32_e32 v195, 0xffff0000, v195
	v_max_f32_e32 v227, 0x219392ef, v5
	v_lshlrev_b32_e32 v199, 16, v196
	v_max_f32_e32 v194, 0x219392ef, v194
	v_and_b32_e32 v196, 0xffff0000, v196
	v_max_f32_e32 v195, 0x219392ef, v195
	v_lshlrev_b32_e32 v201, 16, v197
	v_max_f32_e32 v232, 0x219392ef, v199
	v_and_b32_e32 v197, 0xffff0000, v197
	v_max_f32_e32 v233, 0x219392ef, v196
	v_max_f32_e32 v196, 0x219392ef, v201
	v_max_f32_e32 v3, v197, v197
	s_and_b64 vcc, exec, s[42:43]
	v_max_f32_e32 v197, 0x219392ef, v3
	s_cbranch_vccnz .LBB0_247
	v_lshlrev_b32_e32 v3, 16, v162
	v_and_b32_e32 v5, 0xffff0000, v162
	v_max_f32_e32 v3, 0x219392ef, v3
	v_rcp_f32_e32 v162, v3
	v_lshlrev_b32_e32 v199, 16, v163
	v_max_f32_e32 v3, 0x219392ef, v5
	v_and_b32_e32 v201, 0xffff0000, v163
	v_rcp_f32_e32 v163, v3
	v_max_f32_e32 v3, 0x219392ef, v199
	v_lshlrev_b32_e32 v208, 16, v164
	v_and_b32_e32 v209, 0xffff0000, v164
	v_rcp_f32_e32 v164, v3
	v_max_f32_e32 v3, 0x219392ef, v201
	v_lshlrev_b32_e32 v210, 16, v165
	v_and_b32_e32 v211, 0xffff0000, v165
	v_rcp_f32_e32 v165, v3
	v_max_f32_e32 v3, 0x219392ef, v208
	v_rcp_f32_e32 v208, v3
	v_max_f32_e32 v3, 0x219392ef, v209
	v_rcp_f32_e32 v209, v3
	v_max_f32_e32 v3, 0x219392ef, v210
	v_rcp_f32_e32 v210, v3
	v_max_f32_e32 v3, 0x219392ef, v211
	v_rcp_f32_e32 v211, v3
	v_pk_mul_f32 v[226:227], v[226:227], v[162:163]
	v_pk_mul_f32 v[194:195], v[194:195], v[164:165]
	v_pk_mul_f32 v[232:233], v[232:233], v[208:209]
	v_pk_mul_f32 v[196:197], v[196:197], v[210:211]

; __device__ __forceinline__ float bflo(unsigned w) { return __uint_as_float(w << 16); }
; __device__ __forceinline__ float bfhi(unsigned w) { return __uint_as_float(w & 0xffff0000u); }
;     __device__ __forceinline__ bool fused(f32x4 (&acc)[2][2][4][2], const Unit& u, int wr, int wc, int fr, int fq) const {
;     ...
;                     const u32x4 ga = gav[m][bj]; float s[8];
;                     s[0] = bflo(ga.x); s[1] = bfhi(ga.x); s[2] = bflo(ga.y); s[3] = bfhi(ga.y); s[4] = bflo(ga.z); s[5] = bfhi(ga.z); s[6] = bflo(ga.w); s[7] = bfhi(ga.w);
; #pragma unroll
;                     for (int j = 0; j < 8; ++j) s[j] = fmaxf(s[j], 1e-18f);
;                     if (br < 2) { const u32x4 gb = gbv[m][bj]; float d[8];
;                         d[0] = bflo(gb.x); d[1] = bfhi(gb.x); d[2] = bflo(gb.y); d[3] = bfhi(gb.y); d[4] = bflo(gb.z); d[5] = bfhi(gb.z); d[6] = bflo(gb.w); d[7] = bfhi(gb.w);
; #pragma unroll
;                         for (int j = 0; j < 8; ++j) s[j] *= __builtin_amdgcn_rcpf(fmaxf(d[j], 1e-18f)); }
;                     f32x4 v0 = acc[ai][bj][m][0], v1 = acc[ai][bj][m][1];
;                     v0[0] *= s[0]; v0[1] *= s[1]; v0[2] *= s[2]; v0[3] *= s[3]; v1[0] *= s[4]; v1[1] *= s[5]; v1[2] *= s[6]; v1[3] *= s[7];
;                     if (br < 2) { acc[ai][bj][m][0] = v0; acc[ai][bj][m][1] = v1; }
.LBB0_250:
	s_waitcnt vmcnt(6)
	v_lshlrev_b32_e32 v3, 16, v190
	v_and_b32_e32 v5, 0xffff0000, v190
	v_lshlrev_b32_e32 v162, 16, v191
	v_max_f32_e32 v190, 0x219392ef, v3
	v_and_b32_e32 v163, 0xffff0000, v191
	v_max_f32_e32 v191, 0x219392ef, v5
	v_lshlrev_b32_e32 v164, 16, v192
	v_max_f32_e32 v162, 0x219392ef, v162
	v_and_b32_e32 v165, 0xffff0000, v192
	v_max_f32_e32 v163, 0x219392ef, v163
	v_lshlrev_b32_e32 v194, 16, v193
	v_max_f32_e32 v192, 0x219392ef, v164
	v_and_b32_e32 v195, 0xffff0000, v193
	v_max_f32_e32 v193, 0x219392ef, v165
	s_andn2_b64 vcc, exec, s[4:5]
	v_max_f32_e32 v164, 0x219392ef, v194
	v_max_f32_e32 v3, v195, v195
	s_and_b64 vcc, exec, s[42:43]
	v_max_f32_e32 v165, 0x219392ef, v3
	s_cbranch_vccnz .LBB0_252
	v_lshlrev_b32_e32 v3, 16, v158
	v_and_b32_e32 v5, 0xffff0000, v158
	v_max_f32_e32 v3, 0x219392ef, v3
	v_rcp_f32_e32 v158, v3
	v_lshlrev_b32_e32 v194, 16, v159
	v_max_f32_e32 v3, 0x219392ef, v5
	v_and_b32_e32 v195, 0xffff0000, v159
	v_rcp_f32_e32 v159, v3
	v_max_f32_e32 v3, 0x219392ef, v194
	v_lshlrev_b32_e32 v196, 16, v160
	v_and_b32_e32 v197, 0xffff0000, v160
	v_rcp_f32_e32 v160, v3
	v_max_f32_e32 v3, 0x219392ef, v195
	v_lshlrev_b32_e32 v199, 16, v161
	v_and_b32_e32 v201, 0xffff0000, v161
	v_rcp_f32_e32 v161, v3
	v_max_f32_e32 v3, 0x219392ef, v196
	v_rcp_f32_e32 v194, v3
	v_max_f32_e32 v3, 0x219392ef, v197
	v_rcp_f32_e32 v195, v3
	v_max_f32_e32 v3, 0x219392ef, v199
	v_rcp_f32_e32 v196, v3
	v_max_f32_e32 v3, 0x219392ef, v201
	v_rcp_f32_e32 v197, v3
	v_pk_mul_f32 v[190:191], v[190:191], v[158:159]
	v_pk_mul_f32 v[162:163], v[162:163], v[160:161]
	v_pk_mul_f32 v[192:193], v[192:193], v[194:195]
	v_pk_mul_f32 v[164:165], v[164:165], v[196:197]

; __device__ __forceinline__ float bflo(unsigned w) { return __uint_as_float(w << 16); }
; __device__ __forceinline__ float bfhi(unsigned w) { return __uint_as_float(w & 0xffff0000u); }
;     __device__ __forceinline__ bool fused(f32x4 (&acc)[2][2][4][2], const Unit& u, int wr, int wc, int fr, int fq) const {
;     ...
;                     const u32x4 ga = gav[m][bj]; float s[8];
;                     s[0] = bflo(ga.x); s[1] = bfhi(ga.x); s[2] = bflo(ga.y); s[3] = bfhi(ga.y); s[4] = bflo(ga.z); s[5] = bfhi(ga.z); s[6] = bflo(ga.w); s[7] = bfhi(ga.w);
; #pragma unroll
;                     for (int j = 0; j < 8; ++j) s[j] = fmaxf(s[j], 1e-18f);
;                     if (br < 2) { const u32x4 gb = gbv[m][bj]; float d[8];
;                         d[0] = bflo(gb.x); d[1] = bfhi(gb.x); d[2] = bflo(gb.y); d[3] = bfhi(gb.y); d[4] = bflo(gb.z); d[5] = bfhi(gb.z); d[6] = bflo(gb.w); d[7] = bfhi(gb.w);
; #pragma unroll
;                         for (int j = 0; j < 8; ++j) s[j] *= __builtin_amdgcn_rcpf(fmaxf(d[j], 1e-18f)); }
;                     f32x4 v0 = acc[ai][bj][m][0], v1 = acc[ai][bj][m][1];
;                     v0[0] *= s[0]; v0[1] *= s[1]; v0[2] *= s[2]; v0[3] *= s[3]; v1[0] *= s[4]; v1[1] *= s[5]; v1[2] *= s[6]; v1[3] *= s[7];
;                     if (br < 2) { acc[ai][bj][m][0] = v0; acc[ai][bj][m][1] = v1; }
.LBB0_255:
	s_waitcnt vmcnt(5)
	v_lshlrev_b32_e32 v3, 16, v186
	v_and_b32_e32 v5, 0xffff0000, v186
	v_lshlrev_b32_e32 v158, 16, v187
	v_max_f32_e32 v164, 0x219392ef, v3
	v_and_b32_e32 v159, 0xffff0000, v187
	v_max_f32_e32 v165, 0x219392ef, v5
	v_lshlrev_b32_e32 v160, 16, v188
	v_max_f32_e32 v158, 0x219392ef, v158
	v_and_b32_e32 v161, 0xffff0000, v188
	v_max_f32_e32 v159, 0x219392ef, v159
	v_lshlrev_b32_e32 v162, 16, v189
	v_max_f32_e32 v186, 0x219392ef, v160
	v_and_b32_e32 v163, 0xffff0000, v189
	v_max_f32_e32 v187, 0x219392ef, v161
	s_andn2_b64 vcc, exec, s[4:5]
	v_max_f32_e32 v160, 0x219392ef, v162
	v_max_f32_e32 v3, v163, v163
	s_and_b64 vcc, exec, s[42:43]
	v_max_f32_e32 v161, 0x219392ef, v3
	s_cbranch_vccnz .LBB0_257
	v_lshlrev_b32_e32 v3, 16, v154
	v_and_b32_e32 v5, 0xffff0000, v154
	v_max_f32_e32 v3, 0x219392ef, v3
	v_rcp_f32_e32 v154, v3
	v_lshlrev_b32_e32 v162, 16, v155
	v_max_f32_e32 v3, 0x219392ef, v5
	v_and_b32_e32 v163, 0xffff0000, v155
	v_rcp_f32_e32 v155, v3
	v_max_f32_e32 v3, 0x219392ef, v162
	v_lshlrev_b32_e32 v188, 16, v156
	v_and_b32_e32 v189, 0xffff0000, v156
	v_rcp_f32_e32 v156, v3
	v_max_f32_e32 v3, 0x219392ef, v163
	v_lshlrev_b32_e32 v190, 16, v157
	v_and_b32_e32 v191, 0xffff0000, v157
	v_rcp_f32_e32 v157, v3
	v_max_f32_e32 v3, 0x219392ef, v188
	v_rcp_f32_e32 v162, v3
	v_max_f32_e32 v3, 0x219392ef, v189
	v_rcp_f32_e32 v163, v3
	v_max_f32_e32 v3, 0x219392ef, v190
	v_rcp_f32_e32 v188, v3
	v_max_f32_e32 v3, 0x219392ef, v191
	v_rcp_f32_e32 v189, v3
	v_pk_mul_f32 v[164:165], v[164:165], v[154:155]
	v_pk_mul_f32 v[158:159], v[158:159], v[156:157]
	v_pk_mul_f32 v[186:187], v[186:187], v[162:163]
	v_pk_mul_f32 v[160:161], v[160:161], v[188:189]

; __device__ __forceinline__ float bflo(unsigned w) { return __uint_as_float(w << 16); }
; __device__ __forceinline__ float bfhi(unsigned w) { return __uint_as_float(w & 0xffff0000u); }
;     __device__ __forceinline__ bool fused(f32x4 (&acc)[2][2][4][2], const Unit& u, int wr, int wc, int fr, int fq) const {
;     ...
;                     const u32x4 ga = gav[m][bj]; float s[8];
;                     s[0] = bflo(ga.x); s[1] = bfhi(ga.x); s[2] = bflo(ga.y); s[3] = bfhi(ga.y); s[4] = bflo(ga.z); s[5] = bfhi(ga.z); s[6] = bflo(ga.w); s[7] = bfhi(ga.w);
; #pragma unroll
;                     for (int j = 0; j < 8; ++j) s[j] = fmaxf(s[j], 1e-18f);
;                     if (br < 2) { const u32x4 gb = gbv[m][bj]; float d[8];
;                         d[0] = bflo(gb.x); d[1] = bfhi(gb.x); d[2] = bflo(gb.y); d[3] = bfhi(gb.y); d[4] = bflo(gb.z); d[5] = bfhi(gb.z); d[6] = bflo(gb.w); d[7] = bfhi(gb.w);
; #pragma unroll
;                         for (int j = 0; j < 8; ++j) s[j] *= __builtin_amdgcn_rcpf(fmaxf(d[j], 1e-18f)); }
;                     f32x4 v0 = acc[ai][bj][m][0], v1 = acc[ai][bj][m][1];
;                     v0[0] *= s[0]; v0[1] *= s[1]; v0[2] *= s[2]; v0[3] *= s[3]; v1[0] *= s[4]; v1[1] *= s[5]; v1[2] *= s[6]; v1[3] *= s[7];
;                     if (br < 2) { acc[ai][bj][m][0] = v0; acc[ai][bj][m][1] = v1; }
.LBB0_260:
	s_waitcnt vmcnt(4)
	v_lshlrev_b32_e32 v3, 16, v182
	v_and_b32_e32 v5, 0xffff0000, v182
	v_lshlrev_b32_e32 v154, 16, v183
	v_max_f32_e32 v158, 0x219392ef, v3
	v_and_b32_e32 v155, 0xffff0000, v183
	v_max_f32_e32 v159, 0x219392ef, v5
	v_lshlrev_b32_e32 v156, 16, v184
	v_max_f32_e32 v154, 0x219392ef, v154
	v_and_b32_e32 v157, 0xffff0000, v184
	v_max_f32_e32 v155, 0x219392ef, v155
	v_lshlrev_b32_e32 v164, 16, v185
	v_max_f32_e32 v160, 0x219392ef, v156
	v_and_b32_e32 v165, 0xffff0000, v185
	v_max_f32_e32 v161, 0x219392ef, v157
	s_andn2_b64 vcc, exec, s[4:5]
	v_max_f32_e32 v156, 0x219392ef, v164
	v_max_f32_e32 v3, v165, v165
	s_and_b64 vcc, exec, s[42:43]
	v_max_f32_e32 v157, 0x219392ef, v3
	s_cbranch_vccnz .LBB0_262
	v_lshlrev_b32_e32 v3, 16, v150
	v_and_b32_e32 v5, 0xffff0000, v150
	v_max_f32_e32 v3, 0x219392ef, v3
	v_rcp_f32_e32 v150, v3
	v_lshlrev_b32_e32 v164, 16, v151
	v_max_f32_e32 v3, 0x219392ef, v5
	v_and_b32_e32 v165, 0xffff0000, v151
	v_rcp_f32_e32 v151, v3
	v_max_f32_e32 v3, 0x219392ef, v164
	v_lshlrev_b32_e32 v182, 16, v152
	v_and_b32_e32 v183, 0xffff0000, v152
	v_rcp_f32_e32 v152, v3
	v_max_f32_e32 v3, 0x219392ef, v165
	v_lshlrev_b32_e32 v184, 16, v153
	v_and_b32_e32 v185, 0xffff0000, v153
	v_rcp_f32_e32 v153, v3
	v_max_f32_e32 v3, 0x219392ef, v182
	v_rcp_f32_e32 v164, v3
	v_max_f32_e32 v3, 0x219392ef, v183
	v_rcp_f32_e32 v165, v3
	v_max_f32_e32 v3, 0x219392ef, v184
	v_rcp_f32_e32 v182, v3
	v_max_f32_e32 v3, 0x219392ef, v185
	v_rcp_f32_e32 v183, v3
	v_pk_mul_f32 v[158:159], v[158:159], v[150:151]
	v_pk_mul_f32 v[154:155], v[154:155], v[152:153]
	v_pk_mul_f32 v[160:161], v[160:161], v[164:165]
	v_pk_mul_f32 v[156:157], v[156:157], v[182:183]

; __device__ __forceinline__ float bflo(unsigned w) { return __uint_as_float(w << 16); }
; __device__ __forceinline__ float bfhi(unsigned w) { return __uint_as_float(w & 0xffff0000u); }
;     __device__ __forceinline__ bool fused(f32x4 (&acc)[2][2][4][2], const Unit& u, int wr, int wc, int fr, int fq) const {
;     ...
;                     const u32x4 ga = gav[m][bj]; float s[8];
;                     s[0] = bflo(ga.x); s[1] = bfhi(ga.x); s[2] = bflo(ga.y); s[3] = bfhi(ga.y); s[4] = bflo(ga.z); s[5] = bfhi(ga.z); s[6] = bflo(ga.w); s[7] = bfhi(ga.w);
; #pragma unroll
;                     for (int j = 0; j < 8; ++j) s[j] = fmaxf(s[j], 1e-18f);
;                     if (br < 2) { const u32x4 gb = gbv[m][bj]; float d[8];
;                         d[0] = bflo(gb.x); d[1] = bfhi(gb.x); d[2] = bflo(gb.y); d[3] = bfhi(gb.y); d[4] = bflo(gb.z); d[5] = bfhi(gb.z); d[6] = bflo(gb.w); d[7] = bfhi(gb.w);
; #pragma unroll
;                         for (int j = 0; j < 8; ++j) s[j] *= __builtin_amdgcn_rcpf(fmaxf(d[j], 1e-18f)); }
;                     f32x4 v0 = acc[ai][bj][m][0], v1 = acc[ai][bj][m][1];
;                     v0[0] *= s[0]; v0[1] *= s[1]; v0[2] *= s[2]; v0[3] *= s[3]; v1[0] *= s[4]; v1[1] *= s[5]; v1[2] *= s[6]; v1[3] *= s[7];
;                     if (br < 2) { acc[ai][bj][m][0] = v0; acc[ai][bj][m][1] = v1; }
.LBB0_265:
	s_waitcnt vmcnt(3)
	v_lshlrev_b32_e32 v3, 16, v178
	v_and_b32_e32 v5, 0xffff0000, v178
	v_lshlrev_b32_e32 v150, 16, v179
	v_max_f32_e32 v156, 0x219392ef, v3
	v_and_b32_e32 v151, 0xffff0000, v179
	v_max_f32_e32 v157, 0x219392ef, v5
	v_lshlrev_b32_e32 v152, 16, v180
	v_max_f32_e32 v150, 0x219392ef, v150
	v_and_b32_e32 v153, 0xffff0000, v180
	v_max_f32_e32 v151, 0x219392ef, v151
	v_lshlrev_b32_e32 v154, 16, v181
	v_max_f32_e32 v158, 0x219392ef, v152
	v_and_b32_e32 v155, 0xffff0000, v181
	v_max_f32_e32 v159, 0x219392ef, v153
	s_andn2_b64 vcc, exec, s[4:5]
	v_max_f32_e32 v152, 0x219392ef, v154
	v_max_f32_e32 v3, v155, v155
	s_and_b64 vcc, exec, s[42:43]
	v_max_f32_e32 v153, 0x219392ef, v3
	s_cbranch_vccnz .LBB0_267
	v_lshlrev_b32_e32 v3, 16, v146
	v_and_b32_e32 v5, 0xffff0000, v146
	v_max_f32_e32 v3, 0x219392ef, v3
	v_rcp_f32_e32 v146, v3
	v_lshlrev_b32_e32 v154, 16, v147
	v_max_f32_e32 v3, 0x219392ef, v5
	v_and_b32_e32 v155, 0xffff0000, v147
	v_rcp_f32_e32 v147, v3
	v_max_f32_e32 v3, 0x219392ef, v154
	v_lshlrev_b32_e32 v160, 16, v148
	v_and_b32_e32 v161, 0xffff0000, v148
	v_rcp_f32_e32 v148, v3
	v_max_f32_e32 v3, 0x219392ef, v155
	v_lshlrev_b32_e32 v162, 16, v149
	v_and_b32_e32 v163, 0xffff0000, v149
	v_rcp_f32_e32 v149, v3
	v_max_f32_e32 v3, 0x219392ef, v160
	v_rcp_f32_e32 v154, v3
	v_max_f32_e32 v3, 0x219392ef, v161
	v_rcp_f32_e32 v155, v3
	v_max_f32_e32 v3, 0x219392ef, v162
	v_rcp_f32_e32 v160, v3
	v_max_f32_e32 v3, 0x219392ef, v163
	v_rcp_f32_e32 v161, v3
	v_pk_mul_f32 v[156:157], v[156:157], v[146:147]
	v_pk_mul_f32 v[150:151], v[150:151], v[148:149]
	v_pk_mul_f32 v[158:159], v[158:159], v[154:155]
	v_pk_mul_f32 v[152:153], v[152:153], v[160:161]

; __device__ __forceinline__ float bflo(unsigned w) { return __uint_as_float(w << 16); }
; __device__ __forceinline__ float bfhi(unsigned w) { return __uint_as_float(w & 0xffff0000u); }
;     __device__ __forceinline__ bool fused(f32x4 (&acc)[2][2][4][2], const Unit& u, int wr, int wc, int fr, int fq) const {
;     ...
;                     const u32x4 ga = gav[m][bj]; float s[8];
;                     s[0] = bflo(ga.x); s[1] = bfhi(ga.x); s[2] = bflo(ga.y); s[3] = bfhi(ga.y); s[4] = bflo(ga.z); s[5] = bfhi(ga.z); s[6] = bflo(ga.w); s[7] = bfhi(ga.w);
; #pragma unroll
;                     for (int j = 0; j < 8; ++j) s[j] = fmaxf(s[j], 1e-18f);
;                     if (br < 2) { const u32x4 gb = gbv[m][bj]; float d[8];
;                         d[0] = bflo(gb.x); d[1] = bfhi(gb.x); d[2] = bflo(gb.y); d[3] = bfhi(gb.y); d[4] = bflo(gb.z); d[5] = bfhi(gb.z); d[6] = bflo(gb.w); d[7] = bfhi(gb.w);
; #pragma unroll
;                         for (int j = 0; j < 8; ++j) s[j] *= __builtin_amdgcn_rcpf(fmaxf(d[j], 1e-18f)); }
;                     f32x4 v0 = acc[ai][bj][m][0], v1 = acc[ai][bj][m][1];
;                     v0[0] *= s[0]; v0[1] *= s[1]; v0[2] *= s[2]; v0[3] *= s[3]; v1[0] *= s[4]; v1[1] *= s[5]; v1[2] *= s[6]; v1[3] *= s[7];
;                     if (br < 2) { acc[ai][bj][m][0] = v0; acc[ai][bj][m][1] = v1; }
.LBB0_270:
	s_waitcnt vmcnt(2)
	v_lshlrev_b32_e32 v3, 16, v174
	v_and_b32_e32 v5, 0xffff0000, v174
	v_lshlrev_b32_e32 v146, 16, v175
	v_max_f32_e32 v150, 0x219392ef, v3
	v_and_b32_e32 v147, 0xffff0000, v175
	v_max_f32_e32 v151, 0x219392ef, v5
	v_lshlrev_b32_e32 v148, 16, v176
	v_max_f32_e32 v146, 0x219392ef, v146
	v_and_b32_e32 v149, 0xffff0000, v176
	v_max_f32_e32 v147, 0x219392ef, v147
	v_lshlrev_b32_e32 v156, 16, v177
	v_max_f32_e32 v152, 0x219392ef, v148
	v_and_b32_e32 v157, 0xffff0000, v177
	v_max_f32_e32 v153, 0x219392ef, v149
	s_andn2_b64 vcc, exec, s[4:5]
	v_max_f32_e32 v148, 0x219392ef, v156
	v_max_f32_e32 v3, v157, v157
	s_and_b64 vcc, exec, s[42:43]
	v_max_f32_e32 v149, 0x219392ef, v3
	s_cbranch_vccnz .LBB0_272
	v_lshlrev_b32_e32 v3, 16, v142
	v_and_b32_e32 v5, 0xffff0000, v142
	v_max_f32_e32 v3, 0x219392ef, v3
	v_rcp_f32_e32 v142, v3
	v_lshlrev_b32_e32 v156, 16, v143
	v_max_f32_e32 v3, 0x219392ef, v5
	v_and_b32_e32 v157, 0xffff0000, v143
	v_rcp_f32_e32 v143, v3
	v_max_f32_e32 v3, 0x219392ef, v156
	v_lshlrev_b32_e32 v158, 16, v144
	v_and_b32_e32 v159, 0xffff0000, v144
	v_rcp_f32_e32 v144, v3
	v_max_f32_e32 v3, 0x219392ef, v157
	v_lshlrev_b32_e32 v160, 16, v145
	v_and_b32_e32 v161, 0xffff0000, v145
	v_rcp_f32_e32 v145, v3
	v_max_f32_e32 v3, 0x219392ef, v158
	v_rcp_f32_e32 v156, v3
	v_max_f32_e32 v3, 0x219392ef, v159
	v_rcp_f32_e32 v157, v3
	v_max_f32_e32 v3, 0x219392ef, v160
	v_rcp_f32_e32 v158, v3
	v_max_f32_e32 v3, 0x219392ef, v161
	v_rcp_f32_e32 v159, v3
	v_pk_mul_f32 v[150:151], v[150:151], v[142:143]
	v_pk_mul_f32 v[146:147], v[146:147], v[144:145]
	v_pk_mul_f32 v[152:153], v[152:153], v[156:157]
	v_pk_mul_f32 v[148:149], v[148:149], v[158:159]

; __device__ __forceinline__ float bflo(unsigned w) { return __uint_as_float(w << 16); }
; __device__ __forceinline__ float bfhi(unsigned w) { return __uint_as_float(w & 0xffff0000u); }
;     __device__ __forceinline__ bool fused(f32x4 (&acc)[2][2][4][2], const Unit& u, int wr, int wc, int fr, int fq) const {
;     ...
;                     const u32x4 ga = gav[m][bj]; float s[8];
;                     s[0] = bflo(ga.x); s[1] = bfhi(ga.x); s[2] = bflo(ga.y); s[3] = bfhi(ga.y); s[4] = bflo(ga.z); s[5] = bfhi(ga.z); s[6] = bflo(ga.w); s[7] = bfhi(ga.w);
; #pragma unroll
;                     for (int j = 0; j < 8; ++j) s[j] = fmaxf(s[j], 1e-18f);
;                     if (br < 2) { const u32x4 gb = gbv[m][bj]; float d[8];
;                         d[0] = bflo(gb.x); d[1] = bfhi(gb.x); d[2] = bflo(gb.y); d[3] = bfhi(gb.y); d[4] = bflo(gb.z); d[5] = bfhi(gb.z); d[6] = bflo(gb.w); d[7] = bfhi(gb.w);
; #pragma unroll
;                         for (int j = 0; j < 8; ++j) s[j] *= __builtin_amdgcn_rcpf(fmaxf(d[j], 1e-18f)); }
;                     f32x4 v0 = acc[ai][bj][m][0], v1 = acc[ai][bj][m][1];
;                     v0[0] *= s[0]; v0[1] *= s[1]; v0[2] *= s[2]; v0[3] *= s[3]; v1[0] *= s[4]; v1[1] *= s[5]; v1[2] *= s[6]; v1[3] *= s[7];
;                     if (br < 2) { acc[ai][bj][m][0] = v0; acc[ai][bj][m][1] = v1; }
.LBB0_275:
	s_waitcnt vmcnt(1)
	v_lshlrev_b32_e32 v3, 16, v170
	v_and_b32_e32 v5, 0xffff0000, v170
	v_lshlrev_b32_e32 v142, 16, v171
	v_max_f32_e32 v146, 0x219392ef, v3
	v_and_b32_e32 v143, 0xffff0000, v171
	v_max_f32_e32 v147, 0x219392ef, v5
	v_lshlrev_b32_e32 v144, 16, v172
	v_max_f32_e32 v142, 0x219392ef, v142
	v_and_b32_e32 v145, 0xffff0000, v172
	v_max_f32_e32 v143, 0x219392ef, v143
	v_lshlrev_b32_e32 v150, 16, v173
	v_max_f32_e32 v148, 0x219392ef, v144
	v_and_b32_e32 v151, 0xffff0000, v173
	v_max_f32_e32 v149, 0x219392ef, v145
	s_andn2_b64 vcc, exec, s[4:5]
	v_max_f32_e32 v144, 0x219392ef, v150
	v_max_f32_e32 v3, v151, v151
	s_and_b64 vcc, exec, s[42:43]
	v_max_f32_e32 v145, 0x219392ef, v3
	s_cbranch_vccnz .LBB0_277
	v_lshlrev_b32_e32 v3, 16, v138
	v_and_b32_e32 v5, 0xffff0000, v138
	v_max_f32_e32 v3, 0x219392ef, v3
	v_rcp_f32_e32 v138, v3
	v_lshlrev_b32_e32 v150, 16, v139
	v_max_f32_e32 v3, 0x219392ef, v5
	v_and_b32_e32 v151, 0xffff0000, v139
	v_rcp_f32_e32 v139, v3
	v_max_f32_e32 v3, 0x219392ef, v150
	v_lshlrev_b32_e32 v152, 16, v140
	v_and_b32_e32 v153, 0xffff0000, v140
	v_rcp_f32_e32 v140, v3
	v_max_f32_e32 v3, 0x219392ef, v151
	v_lshlrev_b32_e32 v154, 16, v141
	v_and_b32_e32 v155, 0xffff0000, v141
	v_rcp_f32_e32 v141, v3
	v_max_f32_e32 v3, 0x219392ef, v152
	v_rcp_f32_e32 v150, v3
	v_max_f32_e32 v3, 0x219392ef, v153
	v_rcp_f32_e32 v151, v3
	v_max_f32_e32 v3, 0x219392ef, v154
	v_rcp_f32_e32 v152, v3
	v_max_f32_e32 v3, 0x219392ef, v155
	v_rcp_f32_e32 v153, v3
	v_pk_mul_f32 v[146:147], v[146:147], v[138:139]
	v_pk_mul_f32 v[142:143], v[142:143], v[140:141]
	v_pk_mul_f32 v[148:149], v[148:149], v[150:151]
	v_pk_mul_f32 v[144:145], v[144:145], v[152:153]

; __device__ __forceinline__ float bflo(unsigned w) { return __uint_as_float(w << 16); }
; __device__ __forceinline__ float bfhi(unsigned w) { return __uint_as_float(w & 0xffff0000u); }
;     __device__ __forceinline__ bool fused(f32x4 (&acc)[2][2][4][2], const Unit& u, int wr, int wc, int fr, int fq) const {
;     ...
;                     const u32x4 ga = gav[m][bj]; float s[8];
;                     s[0] = bflo(ga.x); s[1] = bfhi(ga.x); s[2] = bflo(ga.y); s[3] = bfhi(ga.y); s[4] = bflo(ga.z); s[5] = bfhi(ga.z); s[6] = bflo(ga.w); s[7] = bfhi(ga.w);
; #pragma unroll
;                     for (int j = 0; j < 8; ++j) s[j] = fmaxf(s[j], 1e-18f);
;                     if (br < 2) { const u32x4 gb = gbv[m][bj]; float d[8];
;                         d[0] = bflo(gb.x); d[1] = bfhi(gb.x); d[2] = bflo(gb.y); d[3] = bfhi(gb.y); d[4] = bflo(gb.z); d[5] = bfhi(gb.z); d[6] = bflo(gb.w); d[7] = bfhi(gb.w);
; #pragma unroll
;                         for (int j = 0; j < 8; ++j) s[j] *= __builtin_amdgcn_rcpf(fmaxf(d[j], 1e-18f)); }
;                     f32x4 v0 = acc[ai][bj][m][0], v1 = acc[ai][bj][m][1];
;                     v0[0] *= s[0]; v0[1] *= s[1]; v0[2] *= s[2]; v0[3] *= s[3]; v1[0] *= s[4]; v1[1] *= s[5]; v1[2] *= s[6]; v1[3] *= s[7];
;                     if (br < 2) { acc[ai][bj][m][0] = v0; acc[ai][bj][m][1] = v1; }
.LBB0_280:
	s_waitcnt vmcnt(0)
	v_lshlrev_b32_e32 v3, 16, v166
	v_and_b32_e32 v138, 0xffff0000, v166
	v_lshlrev_b32_e32 v139, 16, v167
	v_max_f32_e32 v142, 0x219392ef, v3
	v_and_b32_e32 v140, 0xffff0000, v167
	v_max_f32_e32 v143, 0x219392ef, v138
	v_lshlrev_b32_e32 v141, 16, v168
	v_max_f32_e32 v138, 0x219392ef, v139
	v_and_b32_e32 v145, 0xffff0000, v168
	v_max_f32_e32 v139, 0x219392ef, v140
	v_lshlrev_b32_e32 v146, 16, v169
	v_max_f32_e32 v144, 0x219392ef, v141
	v_and_b32_e32 v147, 0xffff0000, v169
	v_max_f32_e32 v145, 0x219392ef, v145
	s_andn2_b64 vcc, exec, s[4:5]
	v_max_f32_e32 v140, 0x219392ef, v146
	v_max_f32_e32 v3, v147, v147
	s_and_b64 vcc, exec, s[42:43]
	v_max_f32_e32 v141, 0x219392ef, v3
	s_cbranch_vccnz .LBB0_282
	v_lshlrev_b32_e32 v3, 16, v134
	v_and_b32_e32 v146, 0xffff0000, v134
	v_max_f32_e32 v3, 0x219392ef, v3
	v_rcp_f32_e32 v134, v3
	v_lshlrev_b32_e32 v147, 16, v135
	v_max_f32_e32 v3, 0x219392ef, v146
	v_and_b32_e32 v148, 0xffff0000, v135
	v_rcp_f32_e32 v135, v3
	v_max_f32_e32 v3, 0x219392ef, v147
	v_lshlrev_b32_e32 v149, 16, v136
	v_and_b32_e32 v150, 0xffff0000, v136
	v_rcp_f32_e32 v136, v3
	v_max_f32_e32 v3, 0x219392ef, v148
	v_lshlrev_b32_e32 v151, 16, v137
	v_and_b32_e32 v152, 0xffff0000, v137
	v_rcp_f32_e32 v137, v3
	v_max_f32_e32 v3, 0x219392ef, v149
	v_rcp_f32_e32 v146, v3
	v_max_f32_e32 v3, 0x219392ef, v150
	v_rcp_f32_e32 v147, v3
	v_max_f32_e32 v3, 0x219392ef, v151
	v_rcp_f32_e32 v148, v3
	v_max_f32_e32 v3, 0x219392ef, v152
	v_rcp_f32_e32 v149, v3
	v_pk_mul_f32 v[142:143], v[142:143], v[134:135]
	v_pk_mul_f32 v[138:139], v[138:139], v[136:137]
	v_pk_mul_f32 v[144:145], v[144:145], v[146:147]
	v_pk_mul_f32 v[140:141], v[140:141], v[148:149]
